# attention loop edge rotation extended: LDS read base registers for the next tile also computed in front of the barrier
# speedup vs baseline: 1.0081x; 1.0035x over previous
; __device__ __forceinline__ void attn_unit(const TI ti, CArgs& a, int b, int hd, int qrow0, int st_lo, int st_hi, float mfix, float lam, float lam_init, const float* subg, unsigned char* ldsg) {
;     ...
;     ATT_LOAD(st_lo); ATT_STORE(0);
;     __syncthreads();
;     for (int st = st_lo; st < st_hi; ++st) {
;         const int bi = (st - st_lo) & 1;
;         if (st + 1 < st_hi) ATT_LOAD(st + 1);
;     ...
;         if (st + 1 < st_hi) ATT_STORE(bi ^ 1);
;         __syncthreads();
.LBB0_351:
	s_or_b64 exec, exec, s[4:5]
	s_add_i32 s17, s17, 1
	s_setprio 0
	s_xor_b32 s4, s48, 1
	s_mul_i32 s4, s4, 0x8c00
	s_add_i32 s4, s4, 0
	v_add_u32_e32 v82, s4, v147
	v_add_u32_e32 v83, v82, v155
	v_add_u32_e32 v82, v82, v156
	s_add_i32 s37, s37, 64
	s_add_i32 s39, s39, 64
	s_waitcnt vmcnt(3)
	ds_write_b128 v83, v[122:125]
	s_waitcnt vmcnt(2)
	ds_write_b128 v82, v[126:129]
	v_add3_u32 v82, s4, v157, v158
	s_cmp_eq_u32 s17, 35
	s_waitcnt vmcnt(1)
	ds_write_b16 v82, v118 offset:17408
	ds_write_b16_d16_hi v82, v118 offset:17552
	s_waitcnt vmcnt(0)
	ds_write_b16 v82, v114 offset:18560
	ds_write_b16_d16_hi v82, v114 offset:18704
	ds_write_b16 v82, v119 offset:17696
	ds_write_b16_d16_hi v82, v119 offset:17840
	ds_write_b16 v82, v115 offset:18848
	ds_write_b16_d16_hi v82, v115 offset:18992
	ds_write_b16 v82, v120 offset:17984
	ds_write_b16_d16_hi v82, v120 offset:18128
	ds_write_b16 v82, v116 offset:19136
	ds_write_b16_d16_hi v82, v116 offset:19280
	ds_write_b16 v82, v121 offset:18272
	ds_write_b16_d16_hi v82, v121 offset:18416
	ds_write_b16 v82, v117 offset:19424
	ds_write_b16_d16_hi v82, v117 offset:19568
	s_waitcnt lgkmcnt(0)
	s_cmp_eq_u32 s17, 35
	s_cbranch_scc1 .Lattn_last
	s_cmp_lt_u32 s17, 31
	s_cselect_b32 s4, s39, s37
	s_ashr_i32 s5, s4, 31
	s_lshl_b64 s[4:5], s[4:5], 11
	s_add_u32 s33, s27, s4
	s_addc_u32 s36, s34, s5
	v_mov_b32_e32 v82, s33
	v_mov_b32_e32 v83, s36
	s_add_u32 s4, s18, s4
	s_addc_u32 s5, s35, s5
	v_lshl_add_u64 v[82:83], v[140:141], 1, v[82:83]
	v_mov_b32_e32 v84, s4
	v_mov_b32_e32 v85, s5
	v_add_co_u32_e32 v86, vcc, s79, v82
	s_nop 0
	v_addc_co_u32_e32 v87, vcc, 0, v83, vcc
	global_load_dwordx4 v[122:125], v[82:83], off
	global_load_dwordx4 v[126:129], v[86:87], off
	v_lshl_add_u64 v[82:83], v[142:143], 1, v[84:85]
	global_load_dwordx4 v[118:121], v[82:83], off
	global_load_dwordx4 v[114:117], v[82:83], off offset:16
	s_and_b32 s48, s17, 1
	s_mul_i32 s4, s48, 0x8c00
	s_add_i32 s4, s4, 0
	v_add_u32_e32 v82, s4, v160
	v_add_u32_e32 v151, v82, v161
	v_add3_u32 v150, s4, v144, v162
	s_barrier
	s_branch .Lattn_body

; #define LAS __attribute__((address_space(3)))
; #define ATT_QK(SX, sub) do { __builtin_amdgcn_s_setprio(1); _Pragma("unroll") for (int ks = 0; ks < 4; ++ks) { \
;             const bf16x8 kf = *(LAS const bf16x8*)(Bb + KOFF + ((sub) * 32 + r) * 272 + (c * 64 + 16 * ks + 8 * h) * 2); SX = MFMA32(kf, qf[ks], SX); } __builtin_amdgcn_s_setprio(0); } while (0)
; #define ATT_SOFT(SX, P0, P1) do { float p[16]; _Pragma("unroll") for (int i = 0; i < 16; ++i) { p[i] = __builtin_amdgcn_exp2f(SX[i]); lsum += p[i]; } \
;             P0 = pk8f(p[0], p[1], p[2], p[3], p[4], p[5], p[6], p[7]); P1 = pk8f(p[8], p[9], p[10], p[11], p[12], p[13], p[14], p[15]); } while (0)
; #define ATT_PV(sub, P0, P1) do { __builtin_amdgcn_s_setprio(1); _Pragma("unroll") for (int et = 0; et < 4; ++et) { _Pragma("unroll") for (int s = 0; s < 2; ++s) { \
;             const bf16x8 vf = *(LAS const bf16x8*)(Bb + VOFF + (et * 32 + r) * 144 + ((sub) * 32 + 16 * s + 8 * h) * 2); O[et] = MFMA32(vf, s ? P1 : P0, O[et]); } } __builtin_amdgcn_s_setprio(0); } while (0)
; __device__ __forceinline__ void attn_unit(const TI ti, CArgs& a, int b, int hd, int qrow0, int st_lo, int st_hi, float mfix, float lam, float lam_init, const float* subg, unsigned char* ldsg) {
;     ...
;         const int bi = (st - st_lo) & 1;
;         if (st + 1 < st_hi) ATT_LOAD(st + 1);
;         LAS const unsigned char* Bb = L + bi * BUFB;
;         f32x16 Sx0, Sx1; bf16x8 pa0, pa1, pc0, pc1;
; #pragma unroll
;         for (int i = 0; i < 16; ++i) { Sx0[i] = -mfix; Sx1[i] = -mfix; }
;     ...
;         if (w < 4) {
;             ATT_QK(Sx0, 0); ATT_QK(Sx1, 1);
;             __builtin_amdgcn_sched_barrier(0);
;             ATT_SOFT(Sx0, pa0, pa1); ATT_PV(0, pa0, pa1);
;             ATT_SOFT(Sx1, pc0, pc1); ATT_PV(1, pc0, pc1);
.LBB0_352:
	s_cmp_lt_u32 s17, 31
	s_cselect_b32 s4, s39, s37
	s_ashr_i32 s5, s4, 31
	s_lshl_b64 s[4:5], s[4:5], 11
	s_add_u32 s33, s27, s4
	s_addc_u32 s36, s34, s5
	v_mov_b32_e32 v82, s33
	v_mov_b32_e32 v83, s36
	s_add_u32 s4, s18, s4
	s_addc_u32 s5, s35, s5
	v_lshl_add_u64 v[82:83], v[140:141], 1, v[82:83]
	v_mov_b32_e32 v84, s4
	v_mov_b32_e32 v85, s5
	v_add_co_u32_e32 v86, vcc, s79, v82
	s_nop 0
	v_addc_co_u32_e32 v87, vcc, 0, v83, vcc
	global_load_dwordx4 v[122:125], v[82:83], off
	global_load_dwordx4 v[126:129], v[86:87], off
	v_lshl_add_u64 v[82:83], v[142:143], 1, v[84:85]
	global_load_dwordx4 v[118:121], v[82:83], off
	global_load_dwordx4 v[114:117], v[82:83], off offset:16
	s_and_b32 s48, s17, 1
	s_mul_i32 s4, s48, 0x8c00
	s_add_i32 s4, s4, 0
	v_add_u32_e32 v82, s4, v160
	v_add_u32_e32 v151, v82, v161
	v_add3_u32 v150, s4, v144, v162
.Lattn_body:
	s_setprio 1
	ds_read_b128 v[130:133], v151
	s_and_saveexec_b64 s[4:5], s[40:41]
	s_xor_b64 s[4:5], exec, s[4:5]
	s_cbranch_execz .LBB0_354
	ds_read_b128 v[182:185], v151 offset:32
	ds_read_b128 v[198:201], v151 offset:64
	ds_read_b128 v[202:205], v151 offset:96
	ds_read_b128 v[206:209], v151 offset:8704
	ds_read_b128 v[210:213], v151 offset:8736
	ds_read_b128 v[236:239], v151 offset:8768
	ds_read_b128 v[240:243], v151 offset:8800
	s_setprio 1
	s_waitcnt lgkmcnt(7)
	v_mfma_f32_32x32x16_bf16 v[82:97], v[130:133], v[110:113], v[2:17]
	s_waitcnt lgkmcnt(6)
	v_mfma_f32_32x32x16_bf16 v[82:97], v[182:185], v[106:109], v[82:97]
	s_waitcnt lgkmcnt(5)
	v_mfma_f32_32x32x16_bf16 v[82:97], v[198:201], v[102:105], v[82:97]
	s_waitcnt lgkmcnt(4)
	v_mfma_f32_32x32x16_bf16 v[82:97], v[202:205], v[98:101], v[82:97]
	ds_read_b128 v[130:133], v150 offset:17408
	ds_read_b128 v[182:185], v150 offset:17440
	ds_read_b128 v[198:201], v150 offset:22016
	ds_read_b128 v[202:205], v150 offset:22048
	s_waitcnt lgkmcnt(7)
	v_mfma_f32_32x32x16_bf16 v[220:235], v[206:209], v[110:113], v[2:17]
	s_waitcnt lgkmcnt(6)
	v_mfma_f32_32x32x16_bf16 v[220:235], v[210:213], v[106:109], v[220:235]
	s_waitcnt lgkmcnt(5)
	v_mfma_f32_32x32x16_bf16 v[220:235], v[236:239], v[102:105], v[220:235]
	s_waitcnt lgkmcnt(4)
	v_mfma_f32_32x32x16_bf16 v[220:235], v[240:243], v[98:101], v[220:235]
	ds_read_b128 v[206:209], v150 offset:26624
	ds_read_b128 v[210:213], v150 offset:26656
	ds_read_b128 v[236:239], v150 offset:31232
	ds_read_b128 v[240:243], v150 offset:31264
	s_setprio 0
	v_exp_f32_e32 v169, v82
	v_exp_f32_e32 v170, v83
	v_exp_f32_e32 v171, v84
	v_exp_f32_e32 v174, v85
	v_exp_f32_e32 v175, v86
	v_exp_f32_e32 v176, v87
	v_exp_f32_e32 v177, v88
	v_exp_f32_e32 v179, v89
	v_exp_f32_e32 v90, v90
	v_exp_f32_e32 v91, v91
	v_exp_f32_e32 v92, v92
	v_exp_f32_e32 v93, v93
	v_exp_f32_e32 v94, v94
	v_exp_f32_e32 v95, v95
	v_exp_f32_e32 v96, v96
	v_exp_f32_e32 v97, v97
	v_cvt_pk_bf16_f32 v82, v169, v170
	v_cvt_pk_bf16_f32 v83, v171, v174
	v_cvt_pk_bf16_f32 v84, v175, v176
	v_cvt_pk_bf16_f32 v85, v177, v179
	v_cvt_pk_bf16_f32 v86, v90, v91
	v_cvt_pk_bf16_f32 v87, v92, v93
	v_cvt_pk_bf16_f32 v88, v94, v95
	v_cvt_pk_bf16_f32 v89, v96, v97
	s_setprio 1
	s_waitcnt lgkmcnt(7)
	v_mfma_f32_32x32x16_bf16 v[18:33], v[130:133], v[82:85], v[18:33]
	v_add_f32_e32 v0, v169, v0
	v_add_f32_e32 v0, v170, v0
	s_waitcnt lgkmcnt(6)
	v_mfma_f32_32x32x16_bf16 v[18:33], v[182:185], v[86:89], v[18:33]
	v_add_f32_e32 v0, v171, v0
	v_add_f32_e32 v0, v174, v0
	ds_read_b128 v[130:133], v150 offset:17472
	ds_read_b128 v[182:185], v150 offset:17504
	s_waitcnt lgkmcnt(7)
	v_mfma_f32_32x32x16_bf16 v[34:49], v[198:201], v[82:85], v[34:49]
	v_add_f32_e32 v0, v175, v0
	v_add_f32_e32 v0, v176, v0
	s_waitcnt lgkmcnt(6)
	v_mfma_f32_32x32x16_bf16 v[34:49], v[202:205], v[86:89], v[34:49]
	v_add_f32_e32 v0, v177, v0
	v_add_f32_e32 v0, v179, v0
	ds_read_b128 v[198:201], v150 offset:22080
	ds_read_b128 v[202:205], v150 offset:22112
	s_waitcnt lgkmcnt(7)
	v_mfma_f32_32x32x16_bf16 v[66:81], v[206:209], v[82:85], v[66:81]
	v_add_f32_e32 v0, v90, v0
	v_add_f32_e32 v0, v91, v0
	s_waitcnt lgkmcnt(6)
	v_mfma_f32_32x32x16_bf16 v[66:81], v[210:213], v[86:89], v[66:81]
	v_add_f32_e32 v0, v92, v0
	v_add_f32_e32 v0, v93, v0
	ds_read_b128 v[206:209], v150 offset:26688
	ds_read_b128 v[210:213], v150 offset:26720
	s_waitcnt lgkmcnt(7)
	v_mfma_f32_32x32x16_bf16 v[50:65], v[236:239], v[82:85], v[50:65]
	v_add_f32_e32 v0, v94, v0
	v_add_f32_e32 v0, v95, v0
	s_waitcnt lgkmcnt(6)
	v_mfma_f32_32x32x16_bf16 v[50:65], v[240:243], v[86:89], v[50:65]
	v_add_f32_e32 v0, v96, v0
	v_add_f32_e32 v0, v97, v0
	ds_read_b128 v[236:239], v150 offset:31296
	ds_read_b128 v[240:243], v150 offset:31328
	s_setprio 0
	v_exp_f32_e32 v181, v220
	v_exp_f32_e32 v197, v221
	v_exp_f32_e32 v214, v222
	v_exp_f32_e32 v244, v223
	v_exp_f32_e32 v245, v224
	v_exp_f32_e32 v246, v225
	v_exp_f32_e32 v247, v226
	v_exp_f32_e32 v248, v227
	v_exp_f32_e32 v228, v228
	v_exp_f32_e32 v229, v229
	v_exp_f32_e32 v230, v230
	v_exp_f32_e32 v231, v231
	v_exp_f32_e32 v232, v232
	v_exp_f32_e32 v233, v233
	v_exp_f32_e32 v234, v234
	v_exp_f32_e32 v235, v235
	v_cvt_pk_bf16_f32 v220, v181, v197
	v_cvt_pk_bf16_f32 v221, v214, v244
	v_cvt_pk_bf16_f32 v222, v245, v246
	v_cvt_pk_bf16_f32 v223, v247, v248
	v_cvt_pk_bf16_f32 v224, v228, v229
	v_cvt_pk_bf16_f32 v225, v230, v231
	v_cvt_pk_bf16_f32 v226, v232, v233
	v_cvt_pk_bf16_f32 v227, v234, v235
	s_setprio 1
	s_waitcnt lgkmcnt(7)
	v_mfma_f32_32x32x16_bf16 v[18:33], v[130:133], v[220:223], v[18:33]
	v_add_f32_e32 v0, v181, v0
	v_add_f32_e32 v0, v197, v0
	s_waitcnt lgkmcnt(6)
	v_mfma_f32_32x32x16_bf16 v[18:33], v[182:185], v[224:227], v[18:33]
	v_add_f32_e32 v0, v214, v0
	v_add_f32_e32 v0, v244, v0
	s_waitcnt lgkmcnt(5)
	v_mfma_f32_32x32x16_bf16 v[34:49], v[198:201], v[220:223], v[34:49]
	v_add_f32_e32 v0, v245, v0
	v_add_f32_e32 v0, v246, v0
	s_waitcnt lgkmcnt(4)
	v_mfma_f32_32x32x16_bf16 v[34:49], v[202:205], v[224:227], v[34:49]
	v_add_f32_e32 v0, v247, v0
	v_add_f32_e32 v0, v248, v0
	s_waitcnt lgkmcnt(3)
	v_mfma_f32_32x32x16_bf16 v[66:81], v[206:209], v[220:223], v[66:81]
	v_add_f32_e32 v0, v228, v0
	v_add_f32_e32 v0, v229, v0
	s_waitcnt lgkmcnt(2)
	v_mfma_f32_32x32x16_bf16 v[66:81], v[210:213], v[224:227], v[66:81]
	v_add_f32_e32 v0, v230, v0
	v_add_f32_e32 v0, v231, v0
	s_waitcnt lgkmcnt(1)
	v_mfma_f32_32x32x16_bf16 v[50:65], v[236:239], v[220:223], v[50:65]
	v_add_f32_e32 v0, v232, v0
	v_add_f32_e32 v0, v233, v0
	s_waitcnt lgkmcnt(0)
	v_mfma_f32_32x32x16_bf16 v[50:65], v[240:243], v[224:227], v[50:65]
	v_add_f32_e32 v0, v234, v0
	v_add_f32_e32 v0, v235, v0
